# phase 0: the 512 sample rows of the input RMSNorm are spread over all workgroups (2 rows each, waves 0-1, loads requested before the compiled loop) instead of a third pass on workgroups 0-15
# speedup vs baseline: 1.0179x; 1.0179x over previous
.LBB0_19:
	s_cmp_gt_i32 s84, 0
	s_cselect_b64 s[4:5], -1, 0
	s_cmp_lt_i32 s85, 1
	s_cselect_b64 s[6:7], -1, 0
	s_or_b64 s[4:5], s[4:5], s[6:7]
	s_and_b64 vcc, exec, s[4:5]
	s_cbranch_vccnz .LBB0_120
	v_lshrrev_b32_e32 v0, 4, v170
	v_and_b32_e32 v0, 60, v0
	v_lshl_add_u32 v76, s2, 5, v0
	s_movk_i32 s3, 0x4200
	v_cmp_gt_i32_e32 vcc, s3, v76
	s_and_saveexec_b64 s[8:9], vcc
	s_cbranch_execz .LBB0_25
	v_readfirstlane_b32 s100, v170
	s_nop 3
	s_lshr_b32 s100, s100, 6
	s_cmp_lt_u32 s100, 2
	s_cbranch_scc0 .Lmy_p0_a
	s_load_dwordx2 s[98:99], s[0:1], 0x8
	s_lshl_b32 s101, s2, 1
	s_add_i32 s100, s100, s101
	s_lshl_b32 s100, s100, 12
	v_and_b32_e32 v252, 63, v170
	v_lshlrev_b32_e32 v252, 4, v252
	s_waitcnt lgkmcnt(0)
	s_add_u32 s98, s98, s100
	s_addc_u32 s99, s99, 0
	global_load_dwordx4 v[172:175], v252, s[98:99] nt
	global_load_dwordx4 v[176:179], v252, s[98:99] offset:1024 nt
	global_load_dwordx4 v[180:183], v252, s[98:99] offset:2048 nt
	global_load_dwordx4 v[184:187], v252, s[98:99] offset:3072 nt
	s_load_dwordx2 s[98:99], s[0:1], 0x70
	s_waitcnt lgkmcnt(0)
	global_load_dwordx4 v[236:239], v252, s[98:99]
	global_load_dwordx4 v[240:243], v252, s[98:99] offset:1024
	global_load_dwordx4 v[244:247], v252, s[98:99] offset:2048
	global_load_dwordx4 v[248:251], v252, s[98:99] offset:3072
.Lmy_p0_a:
	s_load_dwordx2 s[10:11], s[0:1], 0x70
	s_load_dwordx4 s[4:7], s[0:1], 0x0
	v_lshlrev_b32_e32 v0, 2, v170
	v_and_b32_e32 v78, 0xfc, v0
	v_lshlrev_b32_e32 v16, 2, v78
	s_waitcnt lgkmcnt(0)
	global_load_dwordx4 v[0:3], v16, s[10:11] offset:3072
	global_load_dwordx4 v[4:7], v16, s[10:11] offset:2048
	global_load_dwordx4 v[8:11], v16, s[10:11] offset:1024
	global_load_dwordx4 v[12:15], v16, s[10:11]
	v_mbcnt_lo_u32_b32 v16, -1, 0
	v_mbcnt_hi_u32_b32 v16, -1, v16
	v_and_b32_e32 v17, 64, v16
	v_add_u32_e32 v17, 64, v17
	v_xor_b32_e32 v18, 1, v16
	v_cmp_lt_i32_e32 vcc, v18, v17
	s_load_dwordx2 s[14:15], s[0:1], 0xa0
	v_ashrrev_i32_e32 v77, 31, v76
	v_cndmask_b32_e32 v18, v16, v18, vcc
	v_lshlrev_b32_e32 v79, 2, v18
	v_xor_b32_e32 v18, 2, v16
	v_cmp_lt_i32_e32 vcc, v18, v17
	s_mov_b64 s[12:13], 0x3000
	v_mov_b32_e32 v81, 0
	v_cndmask_b32_e32 v18, v16, v18, vcc
	v_lshlrev_b32_e32 v94, 2, v18
	v_xor_b32_e32 v18, 4, v16
	v_cmp_lt_i32_e32 vcc, v18, v17
	s_lshl_b32 s10, s30, 5
	v_lshlrev_b32_e32 v80, 1, v78
	v_cndmask_b32_e32 v18, v16, v18, vcc
	v_lshlrev_b32_e32 v95, 2, v18
	v_xor_b32_e32 v18, 8, v16
	v_cmp_lt_i32_e32 vcc, v18, v17
	s_waitcnt lgkmcnt(0)
	v_lshl_add_u64 v[82:83], s[14:15], 0, v[80:81]
	s_ashr_i32 s11, s10, 31
	v_cndmask_b32_e32 v18, v16, v18, vcc
	v_lshlrev_b32_e32 v96, 2, v18
	v_xor_b32_e32 v18, 16, v16
	v_cmp_lt_i32_e32 vcc, v18, v17
	v_lshl_add_u64 v[84:85], v[76:77], 0, 1
	s_mov_b64 s[16:17], 0
	v_cndmask_b32_e32 v18, v16, v18, vcc
	v_lshlrev_b32_e32 v97, 2, v18
	v_xor_b32_e32 v18, 32, v16
	v_cmp_lt_i32_e32 vcc, v18, v17
	s_movk_i32 s3, 0x4000
	s_movk_i32 s19, 0x3fff
	v_cndmask_b32_e32 v16, v16, v18, vcc
	v_lshlrev_b32_e32 v98, 2, v16
	v_lshlrev_b64 v[16:17], 12, v[76:77]
	v_lshl_add_u64 v[16:17], s[4:5], 0, v[16:17]
	v_lshl_add_u64 v[86:87], v[16:17], 0, s[12:13]
	v_lshlrev_b64 v[16:17], 11, v[76:77]
	v_and_b32_e32 v18, 63, v170
	v_lshl_or_b32 v16, v18, 3, v16
	v_lshl_add_u64 v[16:17], s[14:15], 0, v[16:17]
	s_mov_b64 s[14:15], 0x1600
	s_lshl_b64 s[12:13], s[10:11], 12
	v_lshl_add_u64 v[88:89], v[16:17], 0, s[14:15]
	s_lshl_b64 s[14:15], s[10:11], 11
	s_mov_b32 s18, 0x3a800000
	s_mov_b32 s20, 0x358637bd
	s_mov_b32 s21, 0x800000
	s_movk_i32 s24, 0xf000
	s_movk_i32 s25, 0x3fff
	s_branch .LBB0_23

.LBB0_25:
	s_or_b64 exec, exec, s[8:9]
	v_readfirstlane_b32 s100, v170
	s_nop 3
	s_lshr_b32 s100, s100, 6
	s_cmp_lt_u32 s100, 2
	s_cbranch_scc0 .Lmy_p0_b
	s_load_dwordx2 s[98:99], s[0:1], 0xa0
	s_lshl_b32 s101, s2, 1
	s_add_i32 s100, s100, s101
	s_lshl_b32 s100, s100, 11
	s_add_u32 s100, s100, 0x2000000
	s_waitcnt lgkmcnt(0)
	s_add_u32 s98, s98, s100
	s_addc_u32 s99, s99, 0
	v_lshrrev_b32_e32 v252, 1, v252
	v_mbcnt_lo_u32_b32 v99, -1, 0
	v_mbcnt_hi_u32_b32 v99, -1, v99
	v_xor_b32_e32 v108, 16, v99
	v_lshlrev_b32_e32 v108, 2, v108
	v_xor_b32_e32 v99, 32, v99
	v_lshlrev_b32_e32 v99, 2, v99
	v_mul_f32_e32 v254, v172, v172
	v_fmac_f32_e32 v254, v173, v173
	v_fmac_f32_e32 v254, v174, v174
	v_fmac_f32_e32 v254, v175, v175
	v_fmac_f32_e32 v254, v176, v176
	v_fmac_f32_e32 v254, v177, v177
	v_fmac_f32_e32 v254, v178, v178
	v_fmac_f32_e32 v254, v179, v179
	v_fmac_f32_e32 v254, v180, v180
	v_fmac_f32_e32 v254, v181, v181
	v_fmac_f32_e32 v254, v182, v182
	v_fmac_f32_e32 v254, v183, v183
	v_fmac_f32_e32 v254, v184, v184
	v_fmac_f32_e32 v254, v185, v185
	v_fmac_f32_e32 v254, v186, v186
	v_fmac_f32_e32 v254, v187, v187
	s_nop 1
	v_add_f32_dpp v254, v254, v254 quad_perm:[1,0,3,2] row_mask:0xf bank_mask:0xf
	s_nop 1
	v_add_f32_dpp v254, v254, v254 quad_perm:[2,3,0,1] row_mask:0xf bank_mask:0xf
	s_nop 1
	v_add_f32_dpp v254, v254, v254 row_half_mirror row_mask:0xf bank_mask:0xf
	s_nop 1
	v_add_f32_dpp v254, v254, v254 row_mirror row_mask:0xf bank_mask:0xf
	ds_bpermute_b32 v253, v108, v254
	s_waitcnt lgkmcnt(0)
	v_add_f32_e32 v254, v254, v253
	ds_bpermute_b32 v253, v99, v254
	s_waitcnt lgkmcnt(0)
	v_add_f32_e32 v254, v254, v253
	v_mov_b32_e32 v253, 0x358637bd
	v_fmac_f32_e32 v253, 0x3a800000, v254
	v_rsq_f32_e32 v254, v253
	s_nop 0
	v_pk_mul_f32 v[172:173], v[172:173], v[254:255] op_sel_hi:[1,0]
	v_pk_mul_f32 v[174:175], v[174:175], v[254:255] op_sel_hi:[1,0]
	v_pk_mul_f32 v[172:173], v[236:237], v[172:173]
	v_pk_mul_f32 v[174:175], v[238:239], v[174:175]
	v_cvt_pk_bf16_f32 v172, v172, v173
	v_cvt_pk_bf16_f32 v173, v174, v175
	global_store_dwordx2 v252, v[172:173], s[98:99]
	v_pk_mul_f32 v[176:177], v[176:177], v[254:255] op_sel_hi:[1,0]
	v_pk_mul_f32 v[178:179], v[178:179], v[254:255] op_sel_hi:[1,0]
	v_pk_mul_f32 v[176:177], v[240:241], v[176:177]
	v_pk_mul_f32 v[178:179], v[242:243], v[178:179]
	v_cvt_pk_bf16_f32 v176, v176, v177
	v_cvt_pk_bf16_f32 v177, v178, v179
	global_store_dwordx2 v252, v[176:177], s[98:99] offset:512
	v_pk_mul_f32 v[180:181], v[180:181], v[254:255] op_sel_hi:[1,0]
	v_pk_mul_f32 v[182:183], v[182:183], v[254:255] op_sel_hi:[1,0]
	v_pk_mul_f32 v[180:181], v[244:245], v[180:181]
	v_pk_mul_f32 v[182:183], v[246:247], v[182:183]
	v_cvt_pk_bf16_f32 v180, v180, v181
	v_cvt_pk_bf16_f32 v181, v182, v183
	global_store_dwordx2 v252, v[180:181], s[98:99] offset:1024
	v_pk_mul_f32 v[184:185], v[184:185], v[254:255] op_sel_hi:[1,0]
	v_pk_mul_f32 v[186:187], v[186:187], v[254:255] op_sel_hi:[1,0]
	v_pk_mul_f32 v[184:185], v[248:249], v[184:185]
	v_pk_mul_f32 v[186:187], v[250:251], v[186:187]
	v_cvt_pk_bf16_f32 v184, v184, v185
	v_cvt_pk_bf16_f32 v185, v186, v187
	global_store_dwordx2 v252, v[184:185], s[98:99] offset:1536
.Lmy_p0_b:
	v_mov_b32_e32 v0, v170
	s_cmpk_gt_i32 s2, 0x9ff
	s_cbranch_scc1 .LBB0_62
	v_lshlrev_b32_e32 v1, 2, v0
	v_and_b32_e32 v2, 4, v0
	v_lshlrev_b32_e32 v3, 3, v0
	s_load_dwordx2 s[12:13], s[0:1], 0x28
	s_load_dwordx2 s[14:15], s[0:1], 0xf0
	v_and_b32_e32 v34, 60, v1
	v_and_or_b32 v35, v3, 24, v2
	v_and_b32_e32 v1, 12, v1
	v_lshlrev_b32_e32 v2, 8, v0
	s_movk_i32 s3, 0x400
	v_and_or_b32 v36, v2, s3, v1
	v_ashrrev_i32_e32 v37, 4, v0
	v_ashrrev_i32_e32 v38, 3, v0
	v_and_b32_e32 v0, 56, v3
	s_movk_i32 s3, 0x104
	v_lshl_add_u32 v1, v34, 2, 0
	v_lshl_add_u32 v2, v38, 2, 0
	v_mul_lo_u32 v3, v37, s3
	v_mul_u32_u24_e32 v4, 0x104, v0
	s_mov_b32 s11, 0
	v_mov_b32_e32 v33, 0
	s_lshl_b32 s3, s30, 1
	s_lshl_b32 s18, s30, 7
	s_lshl_b32 s19, s2, 6
	s_lshl_b32 s20, s30, 8
	s_lshl_b32 s21, s30, 3
	s_lshl_b32 s22, s2, 2
	s_lshl_b32 s23, s30, 4
	s_mul_i32 s24, s30, 3
	s_mul_i32 s25, s30, 0xc0
	s_mul_i32 s26, s30, 12
	s_lshl_b32 s27, s30, 2
	s_lshl_b32 s28, s30, 6
	s_mov_b32 s29, 0xa040
	v_lshlrev_b32_e32 v32, 1, v0
	v_add_u32_e32 v39, v1, v3
	v_add_u32_e32 v40, v2, v4
	s_mov_b32 s16, s2
	s_branch .LBB0_28
